# GEMM main loops: phases merged pairwise (4 load + 4 compute segments of 32 MFMAs, 8 workgroup barriers per iteration instead of 16), counted vmcnt(8)/lgkmcnt waits
# speedup vs baseline: 1.0030x; 1.0007x over previous
; #define PG8_STAGE(bufoff, gbase, voff) do { _Pragma("unroll") for (int _i = 0; _i < 2; ++_i) \
;         __builtin_amdgcn_global_load_lds((const unsigned*)((const char*)(gbase) + (voff)[_i]), (LAS unsigned*)(lds + (bufoff) + ldsw + _i * 8192), 16, 0, 0); } while (0)
; #define PG8_LDA(dst, b, h) do { _Pragma("unroll") for (int m = 0; m < 4; ++m) _Pragma("unroll") for (int k = 0; k < 2; ++k) dst[m][k] = *(const LAS bf16x8*)(lds + PG8_SA(b, h) + aoff + m * 2048 + k * 1024); } while (0)
; #define PG8_LDB(dst, b, h) do { _Pragma("unroll") for (int n = 0; n < 2; ++n) _Pragma("unroll") for (int k = 0; k < 2; ++k) dst[n][k] = *(const LAS bf16x8*)(lds + PG8_SB(b, h) + boff + n * 2048 + k * 1024); } while (0)
; #define PG8_MMA(ai, bj, At, Bt) do { __builtin_amdgcn_s_setprio(1); _Pragma("unroll") for (int m = 0; m < 4; ++m) _Pragma("unroll") for (int n = 0; n < 2; ++n) _Pragma("unroll") for (int k = 0; k < 2; ++k) \
;         acc[ai][bj][m][n] = __builtin_amdgcn_mfma_f32_16x16x32_bf16(Bt[n][k], At[m][k], acc[ai][bj][m][n], 0, 0, 0); __builtin_amdgcn_s_setprio(0); } while (0)
; #define PG8_WAIT_V(n) asm volatile("s_waitcnt vmcnt(" #n ")" ::: "memory")
; #define PG8_WAIT_L(n) asm volatile("s_waitcnt lgkmcnt(" #n ")" ::: "memory")
; template <class Epi>
; __device__ __forceinline__ void gemm_phase(LAS unsigned char* lds, const Gemm g, const StaticOrder& S, const Epi& E) {
;     ...
;         for (int t = 0; t < nt; t += 2) {
;             const bool last = (t == nt - 2);
;             const char* a1 = cA + (size_t)(t + 1) * kstep;
;             const char* a2 = last ? nA : cA + (size_t)(t + 2) * kstep; const char* b2 = last ? nB : cB + (size_t)(t + 2) * kstep;
;             const char* a3 = a2 + kstep; const char* b3 = b2 + kstep;
;             PG8_LDB(B0, 0, 0); PG8_SCHED; PG8_LDA(At, 0, 0); PG8_STAGE(PG8_SA(1, 1), a1 + hstep, voffA);
;             PG8_WAIT_L(8); PG8_BAR; PG8_WAIT_L(0); PG8_MMA(0, 0, At, B0); PG8_BAR; PG8_SCHED;
;             PG8_LDB(B1, 0, 1); PG8_STAGE(PG8_SB(0, 0), b2, voffB);
;             PG8_BAR; PG8_WAIT_L(0); PG8_MMA(0, 1, At, B1); PG8_BAR;
;             PG8_LDA(At, 0, 1); PG8_STAGE(PG8_SA(0, 0), a2, voffA);
;             PG8_BAR; PG8_WAIT_L(0); PG8_MMA(1, 0, At, B0); PG8_BAR; PG8_SCHED;
;             PG8_STAGE(PG8_SB(0, 1), b2 + hstep, voffB);
;             PG8_WAIT_V(6); PG8_BAR; PG8_MMA(1, 1, At, B1); PG8_BAR;
.LBB0_119:
	s_add_i32 s41, s16, 2
	s_add_u32 s18, s14, 0x80
	s_addc_u32 s17, s15, 0
	ds_read_b128 v[128:131], v224
	ds_read_b128 v[132:135], v224 offset:1024
	ds_read_b128 v[136:139], v224 offset:2048
	ds_read_b128 v[140:143], v224 offset:3072
	s_cmp_eq_u32 s31, s16
	s_cselect_b32 s16, s10, s18
	s_cselect_b32 s17, s11, s17
	s_cselect_b32 s19, s13, s40
	s_cselect_b32 s18, s12, s39
	s_add_i32 m0, s24, 0xc000
	ds_read_b128 v[144:147], v247
	ds_read_b128 v[148:151], v247 offset:1024
	ds_read_b128 v[152:155], v247 offset:2048
	ds_read_b128 v[156:159], v247 offset:3072
	ds_read_b128 v[160:163], v247 offset:4096
	ds_read_b128 v[164:167], v247 offset:5120
	ds_read_b128 v[168:171], v247 offset:6144
	global_load_lds_dwordx4 v210, s[14:15]
	s_add_i32 m0, s24, 0xe000
	ds_read_b128 v[172:175], v247 offset:7168
	global_load_lds_dwordx4 v208, s[14:15]
	s_waitcnt lgkmcnt(11)
	ds_read_b128 v[176:179], v225
	ds_read_b128 v[180:183], v225 offset:1024
	ds_read_b128 v[184:187], v225 offset:2048
	ds_read_b128 v[188:191], v225 offset:3072
	s_waitcnt vmcnt(8)
	s_barrier
	s_waitcnt lgkmcnt(4)
	v_mfma_f32_16x16x32_bf16 v[124:127], v[128:131], v[144:147], v[124:127]
	v_mfma_f32_16x16x32_bf16 v[120:123], v[136:139], v[144:147], v[120:123]
	v_mfma_f32_16x16x32_bf16 v[108:111], v[128:131], v[152:155], v[108:111]
	v_mfma_f32_16x16x32_bf16 v[104:107], v[136:139], v[152:155], v[104:107]
	v_mfma_f32_16x16x32_bf16 v[92:95], v[128:131], v[160:163], v[92:95]
	v_mfma_f32_16x16x32_bf16 v[88:91], v[136:139], v[160:163], v[88:91]
	v_mfma_f32_16x16x32_bf16 v[76:79], v[128:131], v[168:171], v[76:79]
	v_mfma_f32_16x16x32_bf16 v[72:75], v[136:139], v[168:171], v[72:75]
	v_mfma_f32_16x16x32_bf16 v[124:127], v[132:135], v[148:151], v[124:127]
	v_mfma_f32_16x16x32_bf16 v[120:123], v[140:143], v[148:151], v[120:123]
	v_mfma_f32_16x16x32_bf16 v[108:111], v[132:135], v[156:159], v[108:111]
	v_mfma_f32_16x16x32_bf16 v[104:107], v[140:143], v[156:159], v[104:107]
	v_mfma_f32_16x16x32_bf16 v[92:95], v[132:135], v[164:167], v[92:95]
	v_mfma_f32_16x16x32_bf16 v[88:91], v[140:143], v[164:167], v[88:91]
	v_mfma_f32_16x16x32_bf16 v[76:79], v[132:135], v[172:175], v[76:79]
	v_mfma_f32_16x16x32_bf16 v[72:75], v[140:143], v[172:175], v[72:75]
	s_waitcnt lgkmcnt(0)
	v_mfma_f32_16x16x32_bf16 v[116:119], v[176:179], v[144:147], v[116:119]
	v_mfma_f32_16x16x32_bf16 v[112:115], v[184:187], v[144:147], v[112:115]
	v_mfma_f32_16x16x32_bf16 v[100:103], v[176:179], v[152:155], v[100:103]
	v_mfma_f32_16x16x32_bf16 v[96:99], v[184:187], v[152:155], v[96:99]
	v_mfma_f32_16x16x32_bf16 v[84:87], v[176:179], v[160:163], v[84:87]
	v_mfma_f32_16x16x32_bf16 v[80:83], v[184:187], v[160:163], v[80:83]
	v_mfma_f32_16x16x32_bf16 v[68:71], v[176:179], v[168:171], v[68:71]
	v_mfma_f32_16x16x32_bf16 v[64:67], v[184:187], v[168:171], v[64:67]
	v_mfma_f32_16x16x32_bf16 v[116:119], v[180:183], v[148:151], v[116:119]
	v_mfma_f32_16x16x32_bf16 v[112:115], v[188:191], v[148:151], v[112:115]
	v_mfma_f32_16x16x32_bf16 v[100:103], v[180:183], v[156:159], v[100:103]
	v_mfma_f32_16x16x32_bf16 v[96:99], v[188:191], v[156:159], v[96:99]
	v_mfma_f32_16x16x32_bf16 v[84:87], v[180:183], v[164:167], v[84:87]
	v_mfma_f32_16x16x32_bf16 v[80:83], v[188:191], v[164:167], v[80:83]
	v_mfma_f32_16x16x32_bf16 v[68:71], v[180:183], v[172:175], v[68:71]
	v_mfma_f32_16x16x32_bf16 v[64:67], v[188:191], v[172:175], v[64:67]
	s_barrier
	s_add_u32 s80, s18, 0x80
	s_addc_u32 s81, s19, 0
	s_mov_b32 m0, s86
	s_nop 0
	global_load_lds_dwordx4 v194, s[18:19]
	s_add_i32 m0, s86, 0x2000
	s_nop 0
	global_load_lds_dwordx4 v206, s[18:19]
	s_mov_b32 m0, s24
	s_add_u32 s82, s16, 0x80
	s_addc_u32 s83, s17, 0
	ds_read_b128 v[144:147], v247 offset:16384
	ds_read_b128 v[148:151], v247 offset:17408
	ds_read_b128 v[152:155], v247 offset:18432
	ds_read_b128 v[156:159], v247 offset:19456
	ds_read_b128 v[160:163], v247 offset:20480
	ds_read_b128 v[164:167], v247 offset:21504
	ds_read_b128 v[168:171], v247 offset:22528
	global_load_lds_dwordx4 v202, s[16:17]
	s_mov_b32 m0, s25
	ds_read_b128 v[172:175], v247 offset:23552
	global_load_lds_dwordx4 v204, s[16:17]
	s_add_u32 s18, s18, s0
	s_addc_u32 s19, s19, s1
	s_add_u32 s84, s18, 0x80
	s_mov_b32 m0, s87
	s_addc_u32 s85, s19, 0
	global_load_lds_dwordx4 v194, s[18:19]
	s_add_i32 m0, s87, 0x2000
	s_nop 0
	global_load_lds_dwordx4 v206, s[18:19]
	s_waitcnt vmcnt(8)
	s_barrier
	s_waitcnt lgkmcnt(0)
	v_mfma_f32_16x16x32_bf16 v[60:63], v[128:131], v[144:147], v[60:63]
	v_mfma_f32_16x16x32_bf16 v[56:59], v[136:139], v[144:147], v[56:59]
	v_mfma_f32_16x16x32_bf16 v[44:47], v[128:131], v[152:155], v[44:47]
	v_mfma_f32_16x16x32_bf16 v[40:43], v[136:139], v[152:155], v[40:43]
	v_mfma_f32_16x16x32_bf16 v[28:31], v[128:131], v[160:163], v[28:31]
	v_mfma_f32_16x16x32_bf16 v[24:27], v[136:139], v[160:163], v[24:27]
	v_mfma_f32_16x16x32_bf16 v[12:15], v[128:131], v[168:171], v[12:15]
	v_mfma_f32_16x16x32_bf16 v[8:11], v[136:139], v[168:171], v[8:11]
	v_mfma_f32_16x16x32_bf16 v[60:63], v[132:135], v[148:151], v[60:63]
	v_mfma_f32_16x16x32_bf16 v[56:59], v[140:143], v[148:151], v[56:59]
	v_mfma_f32_16x16x32_bf16 v[44:47], v[132:135], v[156:159], v[44:47]
	v_mfma_f32_16x16x32_bf16 v[40:43], v[140:143], v[156:159], v[40:43]
	v_mfma_f32_16x16x32_bf16 v[28:31], v[132:135], v[164:167], v[28:31]
	v_mfma_f32_16x16x32_bf16 v[24:27], v[140:143], v[164:167], v[24:27]
	v_mfma_f32_16x16x32_bf16 v[12:15], v[132:135], v[172:175], v[12:15]
	v_mfma_f32_16x16x32_bf16 v[8:11], v[140:143], v[172:175], v[8:11]
	v_mfma_f32_16x16x32_bf16 v[52:55], v[176:179], v[144:147], v[52:55]
	v_mfma_f32_16x16x32_bf16 v[48:51], v[184:187], v[144:147], v[48:51]
	v_mfma_f32_16x16x32_bf16 v[36:39], v[176:179], v[152:155], v[36:39]
	v_mfma_f32_16x16x32_bf16 v[32:35], v[184:187], v[152:155], v[32:35]
	v_mfma_f32_16x16x32_bf16 v[20:23], v[176:179], v[160:163], v[20:23]
	v_mfma_f32_16x16x32_bf16 v[16:19], v[184:187], v[160:163], v[16:19]
	v_mfma_f32_16x16x32_bf16 v[4:7], v[176:179], v[168:171], v[4:7]
	v_mfma_f32_16x16x32_bf16 v[0:3], v[184:187], v[168:171], v[0:3]
	v_mfma_f32_16x16x32_bf16 v[52:55], v[180:183], v[148:151], v[52:55]
	v_mfma_f32_16x16x32_bf16 v[48:51], v[188:191], v[148:151], v[48:51]
	v_mfma_f32_16x16x32_bf16 v[36:39], v[180:183], v[156:159], v[36:39]
	v_mfma_f32_16x16x32_bf16 v[32:35], v[188:191], v[156:159], v[32:35]
	v_mfma_f32_16x16x32_bf16 v[20:23], v[180:183], v[164:167], v[20:23]
	v_mfma_f32_16x16x32_bf16 v[16:19], v[188:191], v[164:167], v[16:19]
	v_mfma_f32_16x16x32_bf16 v[4:7], v[180:183], v[172:175], v[4:7]
	v_mfma_f32_16x16x32_bf16 v[0:3], v[188:191], v[172:175], v[0:3]
	s_barrier
; #define PG8_STAGE(bufoff, gbase, voff) do { _Pragma("unroll") for (int _i = 0; _i < 2; ++_i) \
;         __builtin_amdgcn_global_load_lds((const unsigned*)((const char*)(gbase) + (voff)[_i]), (LAS unsigned*)(lds + (bufoff) + ldsw + _i * 8192), 16, 0, 0); } while (0)
; #define PG8_LDA(dst, b, h) do { _Pragma("unroll") for (int m = 0; m < 4; ++m) _Pragma("unroll") for (int k = 0; k < 2; ++k) dst[m][k] = *(const LAS bf16x8*)(lds + PG8_SA(b, h) + aoff + m * 2048 + k * 1024); } while (0)
; #define PG8_LDB(dst, b, h) do { _Pragma("unroll") for (int n = 0; n < 2; ++n) _Pragma("unroll") for (int k = 0; k < 2; ++k) dst[n][k] = *(const LAS bf16x8*)(lds + PG8_SB(b, h) + boff + n * 2048 + k * 1024); } while (0)
; #define PG8_MMA(ai, bj, At, Bt) do { __builtin_amdgcn_s_setprio(1); _Pragma("unroll") for (int m = 0; m < 4; ++m) _Pragma("unroll") for (int n = 0; n < 2; ++n) _Pragma("unroll") for (int k = 0; k < 2; ++k) \
;         acc[ai][bj][m][n] = __builtin_amdgcn_mfma_f32_16x16x32_bf16(Bt[n][k], At[m][k], acc[ai][bj][m][n], 0, 0, 0); __builtin_amdgcn_s_setprio(0); } while (0)
; #define PG8_WAIT_V(n) asm volatile("s_waitcnt vmcnt(" #n ")" ::: "memory")
; #define PG8_WAIT_L(n) asm volatile("s_waitcnt lgkmcnt(" #n ")" ::: "memory")
; #define PG8_BAR __builtin_amdgcn_s_barrier()
; #define PG8_SCHED __builtin_amdgcn_sched_barrier(0)
; template <class Epi>
; __device__ __forceinline__ void gemm_phase(LAS unsigned char* lds, const Gemm g, const StaticOrder& S, const Epi& E) {
;     ...
;             PG8_LDB(B0, 1, 0); PG8_SCHED; PG8_LDA(At, 1, 0); PG8_STAGE(PG8_SA(0, 1), a2 + hstep, voffA);
;             PG8_WAIT_L(8); PG8_BAR; PG8_WAIT_L(0); PG8_MMA(0, 0, At, B0); PG8_BAR; PG8_SCHED;
;             PG8_LDB(B1, 1, 1); PG8_STAGE(PG8_SB(1, 0), b3, voffB);
;             PG8_BAR; PG8_WAIT_L(0); PG8_MMA(0, 1, At, B1); PG8_BAR;
;             PG8_LDA(At, 1, 1); PG8_STAGE(PG8_SA(1, 0), a3, voffA);
;             PG8_BAR; PG8_WAIT_L(0); PG8_MMA(1, 0, At, B0); PG8_BAR; PG8_SCHED;
;             PG8_STAGE(PG8_SB(1, 1), b3 + hstep, voffB);
;             PG8_WAIT_V(6); PG8_BAR; PG8_MMA(1, 1, At, B1); PG8_BAR;
	ds_read_b128 v[128:131], v226
	ds_read_b128 v[132:135], v226 offset:1024
	ds_read_b128 v[136:139], v226 offset:2048
	ds_read_b128 v[140:143], v226 offset:3072
	s_add_u32 s16, s16, s0
	s_addc_u32 s17, s17, s1
	s_mov_b32 m0, s26
	ds_read_b128 v[144:147], v247 offset:32768
	ds_read_b128 v[148:151], v247 offset:33792
	ds_read_b128 v[152:155], v247 offset:34816
	ds_read_b128 v[156:159], v247 offset:35840
	ds_read_b128 v[160:163], v247 offset:36864
	ds_read_b128 v[164:167], v247 offset:37888
	ds_read_b128 v[168:171], v247 offset:38912
	global_load_lds_dwordx4 v202, s[16:17]
	s_mov_b32 m0, s27
	ds_read_b128 v[172:175], v247 offset:39936
	global_load_lds_dwordx4 v204, s[16:17]
	s_waitcnt lgkmcnt(11)
	ds_read_b128 v[176:179], v227
	ds_read_b128 v[180:183], v227 offset:1024
	ds_read_b128 v[184:187], v227 offset:2048
	ds_read_b128 v[188:191], v227 offset:3072
	s_waitcnt vmcnt(8)
	s_barrier
	s_waitcnt lgkmcnt(4)
	v_mfma_f32_16x16x32_bf16 v[124:127], v[128:131], v[144:147], v[124:127]
	v_mfma_f32_16x16x32_bf16 v[120:123], v[136:139], v[144:147], v[120:123]
	v_mfma_f32_16x16x32_bf16 v[108:111], v[128:131], v[152:155], v[108:111]
	v_mfma_f32_16x16x32_bf16 v[104:107], v[136:139], v[152:155], v[104:107]
	v_mfma_f32_16x16x32_bf16 v[92:95], v[128:131], v[160:163], v[92:95]
	v_mfma_f32_16x16x32_bf16 v[88:91], v[136:139], v[160:163], v[88:91]
	v_mfma_f32_16x16x32_bf16 v[76:79], v[128:131], v[168:171], v[76:79]
	v_mfma_f32_16x16x32_bf16 v[72:75], v[136:139], v[168:171], v[72:75]
	v_mfma_f32_16x16x32_bf16 v[124:127], v[132:135], v[148:151], v[124:127]
	v_mfma_f32_16x16x32_bf16 v[120:123], v[140:143], v[148:151], v[120:123]
	v_mfma_f32_16x16x32_bf16 v[108:111], v[132:135], v[156:159], v[108:111]
	v_mfma_f32_16x16x32_bf16 v[104:107], v[140:143], v[156:159], v[104:107]
	v_mfma_f32_16x16x32_bf16 v[92:95], v[132:135], v[164:167], v[92:95]
	v_mfma_f32_16x16x32_bf16 v[88:91], v[140:143], v[164:167], v[88:91]
	v_mfma_f32_16x16x32_bf16 v[76:79], v[132:135], v[172:175], v[76:79]
	v_mfma_f32_16x16x32_bf16 v[72:75], v[140:143], v[172:175], v[72:75]
	s_waitcnt lgkmcnt(0)
	v_mfma_f32_16x16x32_bf16 v[116:119], v[176:179], v[144:147], v[116:119]
	v_mfma_f32_16x16x32_bf16 v[112:115], v[184:187], v[144:147], v[112:115]
	v_mfma_f32_16x16x32_bf16 v[100:103], v[176:179], v[152:155], v[100:103]
	v_mfma_f32_16x16x32_bf16 v[96:99], v[184:187], v[152:155], v[96:99]
	v_mfma_f32_16x16x32_bf16 v[84:87], v[176:179], v[160:163], v[84:87]
	v_mfma_f32_16x16x32_bf16 v[80:83], v[184:187], v[160:163], v[80:83]
	v_mfma_f32_16x16x32_bf16 v[68:71], v[176:179], v[168:171], v[68:71]
	v_mfma_f32_16x16x32_bf16 v[64:67], v[184:187], v[168:171], v[64:67]
	v_mfma_f32_16x16x32_bf16 v[116:119], v[180:183], v[148:151], v[116:119]
	v_mfma_f32_16x16x32_bf16 v[112:115], v[188:191], v[148:151], v[112:115]
	v_mfma_f32_16x16x32_bf16 v[100:103], v[180:183], v[156:159], v[100:103]
	v_mfma_f32_16x16x32_bf16 v[96:99], v[188:191], v[156:159], v[96:99]
	v_mfma_f32_16x16x32_bf16 v[84:87], v[180:183], v[164:167], v[84:87]
	v_mfma_f32_16x16x32_bf16 v[80:83], v[188:191], v[164:167], v[80:83]
	v_mfma_f32_16x16x32_bf16 v[68:71], v[180:183], v[172:175], v[68:71]
	v_mfma_f32_16x16x32_bf16 v[64:67], v[188:191], v[172:175], v[64:67]
	s_barrier
	s_mov_b32 m0, s88
	s_nop 0
	global_load_lds_dwordx4 v194, s[80:81]
	s_add_i32 m0, s88, 0x2000
	s_nop 0
	global_load_lds_dwordx4 v206, s[80:81]
	s_mov_b32 m0, s28
	ds_read_b128 v[144:147], v247 offset:49152
	ds_read_b128 v[148:151], v247 offset:50176
	ds_read_b128 v[152:155], v247 offset:51200
	ds_read_b128 v[156:159], v247 offset:52224
	ds_read_b128 v[160:163], v247 offset:53248
	ds_read_b128 v[164:167], v247 offset:54272
	ds_read_b128 v[168:171], v247 offset:55296
	global_load_lds_dwordx4 v202, s[82:83]
	s_mov_b32 m0, s29
	ds_read_b128 v[172:175], v247 offset:56320
	global_load_lds_dwordx4 v204, s[82:83]
	s_mov_b32 m0, s89
	s_nop 0
	global_load_lds_dwordx4 v194, s[84:85]
	s_add_i32 m0, s89, 0x2000
	s_nop 0
	global_load_lds_dwordx4 v206, s[84:85]
	s_waitcnt vmcnt(8)
	s_barrier
	s_waitcnt lgkmcnt(0)
	v_mfma_f32_16x16x32_bf16 v[60:63], v[128:131], v[144:147], v[60:63]
	v_mfma_f32_16x16x32_bf16 v[56:59], v[136:139], v[144:147], v[56:59]
	v_mfma_f32_16x16x32_bf16 v[44:47], v[128:131], v[152:155], v[44:47]
	v_mfma_f32_16x16x32_bf16 v[40:43], v[136:139], v[152:155], v[40:43]
	v_mfma_f32_16x16x32_bf16 v[28:31], v[128:131], v[160:163], v[28:31]
	v_mfma_f32_16x16x32_bf16 v[24:27], v[136:139], v[160:163], v[24:27]
	v_mfma_f32_16x16x32_bf16 v[12:15], v[128:131], v[168:171], v[12:15]
	v_mfma_f32_16x16x32_bf16 v[8:11], v[136:139], v[168:171], v[8:11]
	v_mfma_f32_16x16x32_bf16 v[60:63], v[132:135], v[148:151], v[60:63]
	v_mfma_f32_16x16x32_bf16 v[56:59], v[140:143], v[148:151], v[56:59]
	v_mfma_f32_16x16x32_bf16 v[44:47], v[132:135], v[156:159], v[44:47]
	v_mfma_f32_16x16x32_bf16 v[40:43], v[140:143], v[156:159], v[40:43]
	v_mfma_f32_16x16x32_bf16 v[28:31], v[132:135], v[164:167], v[28:31]
	v_mfma_f32_16x16x32_bf16 v[24:27], v[140:143], v[164:167], v[24:27]
	v_mfma_f32_16x16x32_bf16 v[12:15], v[132:135], v[172:175], v[12:15]
	v_mfma_f32_16x16x32_bf16 v[8:11], v[140:143], v[172:175], v[8:11]
	v_mfma_f32_16x16x32_bf16 v[52:55], v[176:179], v[144:147], v[52:55]
	v_mfma_f32_16x16x32_bf16 v[48:51], v[184:187], v[144:147], v[48:51]
	v_mfma_f32_16x16x32_bf16 v[36:39], v[176:179], v[152:155], v[36:39]
	v_mfma_f32_16x16x32_bf16 v[32:35], v[184:187], v[152:155], v[32:35]
	v_mfma_f32_16x16x32_bf16 v[20:23], v[176:179], v[160:163], v[20:23]
	v_mfma_f32_16x16x32_bf16 v[16:19], v[184:187], v[160:163], v[16:19]
	v_mfma_f32_16x16x32_bf16 v[4:7], v[176:179], v[168:171], v[4:7]
	v_mfma_f32_16x16x32_bf16 v[0:3], v[184:187], v[168:171], v[0:3]
	v_mfma_f32_16x16x32_bf16 v[52:55], v[180:183], v[148:151], v[52:55]
	v_mfma_f32_16x16x32_bf16 v[48:51], v[188:191], v[148:151], v[48:51]
	v_mfma_f32_16x16x32_bf16 v[36:39], v[180:183], v[156:159], v[36:39]
	v_mfma_f32_16x16x32_bf16 v[32:35], v[188:191], v[156:159], v[32:35]
	v_mfma_f32_16x16x32_bf16 v[20:23], v[180:183], v[164:167], v[20:23]
	v_mfma_f32_16x16x32_bf16 v[16:19], v[188:191], v[164:167], v[16:19]
	v_mfma_f32_16x16x32_bf16 v[4:7], v[180:183], v[172:175], v[4:7]
	v_mfma_f32_16x16x32_bf16 v[0:3], v[188:191], v[172:175], v[0:3]
	s_add_u32 s39, s39, 0x100
	s_addc_u32 s40, s40, 0
	s_add_u32 s14, s14, 0x100
	s_addc_u32 s15, s15, 0
	s_cmp_ge_i32 s41, s30
	s_mov_b32 s16, s41
	s_barrier
	s_cbranch_scc0 .LBB0_119

; #define PG8_STAGE(bufoff, gbase, voff) do { _Pragma("unroll") for (int _i = 0; _i < 2; ++_i) \
;         __builtin_amdgcn_global_load_lds((const unsigned*)((const char*)(gbase) + (voff)[_i]), (LAS unsigned*)(lds + (bufoff) + ldsw + _i * 8192), 16, 0, 0); } while (0)
; #define PG8_LDA(dst, b, h) do { _Pragma("unroll") for (int m = 0; m < 4; ++m) _Pragma("unroll") for (int k = 0; k < 2; ++k) dst[m][k] = *(const LAS bf16x8*)(lds + PG8_SA(b, h) + aoff + m * 2048 + k * 1024); } while (0)
; #define PG8_LDB(dst, b, h) do { _Pragma("unroll") for (int n = 0; n < 2; ++n) _Pragma("unroll") for (int k = 0; k < 2; ++k) dst[n][k] = *(const LAS bf16x8*)(lds + PG8_SB(b, h) + boff + n * 2048 + k * 1024); } while (0)
; #define PG8_MMA(ai, bj, At, Bt) do { __builtin_amdgcn_s_setprio(1); _Pragma("unroll") for (int m = 0; m < 4; ++m) _Pragma("unroll") for (int n = 0; n < 2; ++n) _Pragma("unroll") for (int k = 0; k < 2; ++k) \
;         acc[ai][bj][m][n] = __builtin_amdgcn_mfma_f32_16x16x32_bf16(Bt[n][k], At[m][k], acc[ai][bj][m][n], 0, 0, 0); __builtin_amdgcn_s_setprio(0); } while (0)
; #define PG8_WAIT_V(n) asm volatile("s_waitcnt vmcnt(" #n ")" ::: "memory")
; #define PG8_WAIT_L(n) asm volatile("s_waitcnt lgkmcnt(" #n ")" ::: "memory")
; template <class Epi>
; __device__ __forceinline__ void gemm_phase(LAS unsigned char* lds, const Gemm g, const StaticOrder& S, const Epi& E) {
;     ...
;         for (int t = 0; t < nt; t += 2) {
;             const bool last = (t == nt - 2);
;             const char* a1 = cA + (size_t)(t + 1) * kstep;
;             const char* a2 = last ? nA : cA + (size_t)(t + 2) * kstep; const char* b2 = last ? nB : cB + (size_t)(t + 2) * kstep;
;             const char* a3 = a2 + kstep; const char* b3 = b2 + kstep;
;             PG8_LDB(B0, 0, 0); PG8_SCHED; PG8_LDA(At, 0, 0); PG8_STAGE(PG8_SA(1, 1), a1 + hstep, voffA);
;             PG8_WAIT_L(8); PG8_BAR; PG8_WAIT_L(0); PG8_MMA(0, 0, At, B0); PG8_BAR; PG8_SCHED;
;             PG8_LDB(B1, 0, 1); PG8_STAGE(PG8_SB(0, 0), b2, voffB);
;             PG8_BAR; PG8_WAIT_L(0); PG8_MMA(0, 1, At, B1); PG8_BAR;
;             PG8_LDA(At, 0, 1); PG8_STAGE(PG8_SA(0, 0), a2, voffA);
;             PG8_BAR; PG8_WAIT_L(0); PG8_MMA(1, 0, At, B0); PG8_BAR; PG8_SCHED;
;             PG8_STAGE(PG8_SB(0, 1), b2 + hstep, voffB);
;             PG8_WAIT_V(6); PG8_BAR; PG8_MMA(1, 1, At, B1); PG8_BAR;
.LBB0_165:
	s_add_i32 s44, s18, 2
	s_add_u32 s20, s16, 0x80
	s_addc_u32 s19, s17, 0
	ds_read_b128 v[138:141], v224
	ds_read_b128 v[152:155], v224 offset:1024
	ds_read_b128 v[156:159], v224 offset:2048
	ds_read_b128 v[160:163], v224 offset:3072
	s_cmp_eq_u32 s35, s18
	s_cselect_b32 s18, s10, s20
	s_cselect_b32 s19, s11, s19
	s_cselect_b32 s21, s13, s43
	s_cselect_b32 s20, s12, s42
	s_add_i32 m0, s27, 0xc000
	ds_read_b128 v[164:167], v150
	ds_read_b128 v[168:171], v150 offset:1024
	ds_read_b128 v[172:175], v150 offset:2048
	ds_read_b128 v[176:179], v150 offset:3072
	ds_read_b128 v[180:183], v150 offset:4096
	ds_read_b128 v[184:187], v150 offset:5120
	ds_read_b128 v[188:191], v150 offset:6144
	global_load_lds_dwordx4 v136, s[16:17]
	s_add_i32 m0, s27, 0xe000
	ds_read_b128 v[202:205], v150 offset:7168
	global_load_lds_dwordx4 v134, s[16:17]
	s_waitcnt lgkmcnt(11)
	ds_read_b128 v[206:209], v225
	ds_read_b128 v[210:213], v225 offset:1024
	ds_read_b128 v[218:221], v225 offset:3072
	ds_read_b128 v[214:217], v225 offset:2048
	s_waitcnt vmcnt(8)
	s_barrier
	s_waitcnt lgkmcnt(4)
	v_mfma_f32_16x16x32_bf16 v[124:127], v[138:141], v[164:167], v[124:127]
	v_mfma_f32_16x16x32_bf16 v[120:123], v[156:159], v[164:167], v[120:123]
	v_mfma_f32_16x16x32_bf16 v[108:111], v[138:141], v[172:175], v[108:111]
	v_mfma_f32_16x16x32_bf16 v[104:107], v[156:159], v[172:175], v[104:107]
	v_mfma_f32_16x16x32_bf16 v[92:95], v[138:141], v[180:183], v[92:95]
	v_mfma_f32_16x16x32_bf16 v[88:91], v[156:159], v[180:183], v[88:91]
	v_mfma_f32_16x16x32_bf16 v[76:79], v[138:141], v[188:191], v[76:79]
	v_mfma_f32_16x16x32_bf16 v[72:75], v[156:159], v[188:191], v[72:75]
	v_mfma_f32_16x16x32_bf16 v[124:127], v[152:155], v[168:171], v[124:127]
	v_mfma_f32_16x16x32_bf16 v[120:123], v[160:163], v[168:171], v[120:123]
	v_mfma_f32_16x16x32_bf16 v[108:111], v[152:155], v[176:179], v[108:111]
	v_mfma_f32_16x16x32_bf16 v[104:107], v[160:163], v[176:179], v[104:107]
	v_mfma_f32_16x16x32_bf16 v[92:95], v[152:155], v[184:187], v[92:95]
	v_mfma_f32_16x16x32_bf16 v[88:91], v[160:163], v[184:187], v[88:91]
	v_mfma_f32_16x16x32_bf16 v[76:79], v[152:155], v[202:205], v[76:79]
	v_mfma_f32_16x16x32_bf16 v[72:75], v[160:163], v[202:205], v[72:75]
	s_waitcnt lgkmcnt(0)
	v_mfma_f32_16x16x32_bf16 v[116:119], v[206:209], v[164:167], v[116:119]
	v_mfma_f32_16x16x32_bf16 v[112:115], v[214:217], v[164:167], v[112:115]
	v_mfma_f32_16x16x32_bf16 v[100:103], v[206:209], v[172:175], v[100:103]
	v_mfma_f32_16x16x32_bf16 v[96:99], v[214:217], v[172:175], v[96:99]
	v_mfma_f32_16x16x32_bf16 v[84:87], v[206:209], v[180:183], v[84:87]
	v_mfma_f32_16x16x32_bf16 v[80:83], v[214:217], v[180:183], v[80:83]
	v_mfma_f32_16x16x32_bf16 v[68:71], v[206:209], v[188:191], v[68:71]
	v_mfma_f32_16x16x32_bf16 v[64:67], v[214:217], v[188:191], v[64:67]
	v_mfma_f32_16x16x32_bf16 v[116:119], v[210:213], v[168:171], v[116:119]
	v_mfma_f32_16x16x32_bf16 v[112:115], v[218:221], v[168:171], v[112:115]
	v_mfma_f32_16x16x32_bf16 v[100:103], v[210:213], v[176:179], v[100:103]
	v_mfma_f32_16x16x32_bf16 v[96:99], v[218:221], v[176:179], v[96:99]
	v_mfma_f32_16x16x32_bf16 v[84:87], v[210:213], v[184:187], v[84:87]
	v_mfma_f32_16x16x32_bf16 v[80:83], v[218:221], v[184:187], v[80:83]
	v_mfma_f32_16x16x32_bf16 v[68:71], v[210:213], v[202:205], v[68:71]
	v_mfma_f32_16x16x32_bf16 v[64:67], v[218:221], v[202:205], v[64:67]
	s_barrier
	s_add_u32 s80, s20, 0x80
	s_addc_u32 s81, s21, 0
	s_mov_b32 m0, s86
	s_nop 0
	global_load_lds_dwordx4 v194, s[20:21]
	s_add_i32 m0, s86, 0x2000
	s_nop 0
	global_load_lds_dwordx4 v132, s[20:21]
	s_mov_b32 m0, s27
	s_add_u32 s82, s18, 0x80
	s_addc_u32 s83, s19, 0
	ds_read_b128 v[164:167], v150 offset:16384
	ds_read_b128 v[168:171], v150 offset:17408
	ds_read_b128 v[172:175], v150 offset:18432
	ds_read_b128 v[176:179], v150 offset:19456
	ds_read_b128 v[180:183], v150 offset:20480
	ds_read_b128 v[184:187], v150 offset:21504
	ds_read_b128 v[188:191], v150 offset:22528
	global_load_lds_dwordx4 v128, s[18:19]
	s_mov_b32 m0, s28
	ds_read_b128 v[202:205], v150 offset:23552
	global_load_lds_dwordx4 v130, s[18:19]
	s_add_u32 s20, s20, s2
	s_addc_u32 s21, s21, s3
	s_add_u32 s84, s20, 0x80
	s_mov_b32 m0, s87
	s_addc_u32 s85, s21, 0
	global_load_lds_dwordx4 v194, s[20:21]
	s_add_i32 m0, s87, 0x2000
	s_nop 0
	global_load_lds_dwordx4 v132, s[20:21]
	s_waitcnt vmcnt(8)
	s_barrier
	s_waitcnt lgkmcnt(0)
	v_mfma_f32_16x16x32_bf16 v[60:63], v[138:141], v[164:167], v[60:63]
	v_mfma_f32_16x16x32_bf16 v[56:59], v[156:159], v[164:167], v[56:59]
	v_mfma_f32_16x16x32_bf16 v[44:47], v[138:141], v[172:175], v[44:47]
	v_mfma_f32_16x16x32_bf16 v[40:43], v[156:159], v[172:175], v[40:43]
	v_mfma_f32_16x16x32_bf16 v[28:31], v[138:141], v[180:183], v[28:31]
	v_mfma_f32_16x16x32_bf16 v[24:27], v[156:159], v[180:183], v[24:27]
	v_mfma_f32_16x16x32_bf16 v[12:15], v[138:141], v[188:191], v[12:15]
	v_mfma_f32_16x16x32_bf16 v[8:11], v[156:159], v[188:191], v[8:11]
	v_mfma_f32_16x16x32_bf16 v[60:63], v[152:155], v[168:171], v[60:63]
	v_mfma_f32_16x16x32_bf16 v[56:59], v[160:163], v[168:171], v[56:59]
	v_mfma_f32_16x16x32_bf16 v[44:47], v[152:155], v[176:179], v[44:47]
	v_mfma_f32_16x16x32_bf16 v[40:43], v[160:163], v[176:179], v[40:43]
	v_mfma_f32_16x16x32_bf16 v[28:31], v[152:155], v[184:187], v[28:31]
	v_mfma_f32_16x16x32_bf16 v[24:27], v[160:163], v[184:187], v[24:27]
	v_mfma_f32_16x16x32_bf16 v[12:15], v[152:155], v[202:205], v[12:15]
	v_mfma_f32_16x16x32_bf16 v[8:11], v[160:163], v[202:205], v[8:11]
	v_mfma_f32_16x16x32_bf16 v[52:55], v[206:209], v[164:167], v[52:55]
	v_mfma_f32_16x16x32_bf16 v[48:51], v[214:217], v[164:167], v[48:51]
	v_mfma_f32_16x16x32_bf16 v[36:39], v[206:209], v[172:175], v[36:39]
	v_mfma_f32_16x16x32_bf16 v[32:35], v[214:217], v[172:175], v[32:35]
	v_mfma_f32_16x16x32_bf16 v[20:23], v[206:209], v[180:183], v[20:23]
	v_mfma_f32_16x16x32_bf16 v[16:19], v[214:217], v[180:183], v[16:19]
	v_mfma_f32_16x16x32_bf16 v[4:7], v[206:209], v[188:191], v[4:7]
	v_mfma_f32_16x16x32_bf16 v[0:3], v[214:217], v[188:191], v[0:3]
	v_mfma_f32_16x16x32_bf16 v[52:55], v[210:213], v[168:171], v[52:55]
	v_mfma_f32_16x16x32_bf16 v[48:51], v[218:221], v[168:171], v[48:51]
	v_mfma_f32_16x16x32_bf16 v[36:39], v[210:213], v[176:179], v[36:39]
	v_mfma_f32_16x16x32_bf16 v[32:35], v[218:221], v[176:179], v[32:35]
	v_mfma_f32_16x16x32_bf16 v[20:23], v[210:213], v[184:187], v[20:23]
	v_mfma_f32_16x16x32_bf16 v[16:19], v[218:221], v[184:187], v[16:19]
	v_mfma_f32_16x16x32_bf16 v[4:7], v[210:213], v[202:205], v[4:7]
	v_mfma_f32_16x16x32_bf16 v[0:3], v[218:221], v[202:205], v[0:3]
	s_barrier
; #define PG8_STAGE(bufoff, gbase, voff) do { _Pragma("unroll") for (int _i = 0; _i < 2; ++_i) \
;         __builtin_amdgcn_global_load_lds((const unsigned*)((const char*)(gbase) + (voff)[_i]), (LAS unsigned*)(lds + (bufoff) + ldsw + _i * 8192), 16, 0, 0); } while (0)
; #define PG8_LDA(dst, b, h) do { _Pragma("unroll") for (int m = 0; m < 4; ++m) _Pragma("unroll") for (int k = 0; k < 2; ++k) dst[m][k] = *(const LAS bf16x8*)(lds + PG8_SA(b, h) + aoff + m * 2048 + k * 1024); } while (0)
; #define PG8_LDB(dst, b, h) do { _Pragma("unroll") for (int n = 0; n < 2; ++n) _Pragma("unroll") for (int k = 0; k < 2; ++k) dst[n][k] = *(const LAS bf16x8*)(lds + PG8_SB(b, h) + boff + n * 2048 + k * 1024); } while (0)
; #define PG8_MMA(ai, bj, At, Bt) do { __builtin_amdgcn_s_setprio(1); _Pragma("unroll") for (int m = 0; m < 4; ++m) _Pragma("unroll") for (int n = 0; n < 2; ++n) _Pragma("unroll") for (int k = 0; k < 2; ++k) \
;         acc[ai][bj][m][n] = __builtin_amdgcn_mfma_f32_16x16x32_bf16(Bt[n][k], At[m][k], acc[ai][bj][m][n], 0, 0, 0); __builtin_amdgcn_s_setprio(0); } while (0)
; #define PG8_WAIT_V(n) asm volatile("s_waitcnt vmcnt(" #n ")" ::: "memory")
; #define PG8_WAIT_L(n) asm volatile("s_waitcnt lgkmcnt(" #n ")" ::: "memory")
; #define PG8_BAR __builtin_amdgcn_s_barrier()
; #define PG8_SCHED __builtin_amdgcn_sched_barrier(0)
; template <class Epi>
; __device__ __forceinline__ void gemm_phase(LAS unsigned char* lds, const Gemm g, const StaticOrder& S, const Epi& E) {
;     ...
;             PG8_LDB(B0, 1, 0); PG8_SCHED; PG8_LDA(At, 1, 0); PG8_STAGE(PG8_SA(0, 1), a2 + hstep, voffA);
;             PG8_WAIT_L(8); PG8_BAR; PG8_WAIT_L(0); PG8_MMA(0, 0, At, B0); PG8_BAR; PG8_SCHED;
;             PG8_LDB(B1, 1, 1); PG8_STAGE(PG8_SB(1, 0), b3, voffB);
;             PG8_BAR; PG8_WAIT_L(0); PG8_MMA(0, 1, At, B1); PG8_BAR;
;             PG8_LDA(At, 1, 1); PG8_STAGE(PG8_SA(1, 0), a3, voffA);
;             PG8_BAR; PG8_WAIT_L(0); PG8_MMA(1, 0, At, B0); PG8_BAR; PG8_SCHED;
;             PG8_STAGE(PG8_SB(1, 1), b3 + hstep, voffB);
;             PG8_WAIT_V(6); PG8_BAR; PG8_MMA(1, 1, At, B1); PG8_BAR;
	ds_read_b128 v[138:141], v226
	ds_read_b128 v[152:155], v226 offset:1024
	ds_read_b128 v[156:159], v226 offset:2048
	ds_read_b128 v[160:163], v226 offset:3072
	s_add_u32 s18, s18, s2
	s_addc_u32 s19, s19, s3
	s_mov_b32 m0, s29
	ds_read_b128 v[164:167], v150 offset:32768
	ds_read_b128 v[168:171], v150 offset:33792
	ds_read_b128 v[172:175], v150 offset:34816
	ds_read_b128 v[176:179], v150 offset:35840
	ds_read_b128 v[180:183], v150 offset:36864
	ds_read_b128 v[184:187], v150 offset:37888
	ds_read_b128 v[188:191], v150 offset:38912
	global_load_lds_dwordx4 v128, s[18:19]
	s_mov_b32 m0, s30
	ds_read_b128 v[202:205], v150 offset:39936
	global_load_lds_dwordx4 v130, s[18:19]
	s_waitcnt lgkmcnt(11)
	ds_read_b128 v[206:209], v227
	ds_read_b128 v[210:213], v227 offset:1024
	ds_read_b128 v[214:217], v227 offset:2048
	ds_read_b128 v[218:221], v227 offset:3072
	s_waitcnt vmcnt(8)
	s_barrier
	s_waitcnt lgkmcnt(4)
	v_mfma_f32_16x16x32_bf16 v[124:127], v[138:141], v[164:167], v[124:127]
	v_mfma_f32_16x16x32_bf16 v[120:123], v[156:159], v[164:167], v[120:123]
	v_mfma_f32_16x16x32_bf16 v[108:111], v[138:141], v[172:175], v[108:111]
	v_mfma_f32_16x16x32_bf16 v[104:107], v[156:159], v[172:175], v[104:107]
	v_mfma_f32_16x16x32_bf16 v[92:95], v[138:141], v[180:183], v[92:95]
	v_mfma_f32_16x16x32_bf16 v[88:91], v[156:159], v[180:183], v[88:91]
	v_mfma_f32_16x16x32_bf16 v[76:79], v[138:141], v[188:191], v[76:79]
	v_mfma_f32_16x16x32_bf16 v[72:75], v[156:159], v[188:191], v[72:75]
	v_mfma_f32_16x16x32_bf16 v[124:127], v[152:155], v[168:171], v[124:127]
	v_mfma_f32_16x16x32_bf16 v[120:123], v[160:163], v[168:171], v[120:123]
	v_mfma_f32_16x16x32_bf16 v[108:111], v[152:155], v[176:179], v[108:111]
	v_mfma_f32_16x16x32_bf16 v[104:107], v[160:163], v[176:179], v[104:107]
	v_mfma_f32_16x16x32_bf16 v[92:95], v[152:155], v[184:187], v[92:95]
	v_mfma_f32_16x16x32_bf16 v[88:91], v[160:163], v[184:187], v[88:91]
	v_mfma_f32_16x16x32_bf16 v[76:79], v[152:155], v[202:205], v[76:79]
	v_mfma_f32_16x16x32_bf16 v[72:75], v[160:163], v[202:205], v[72:75]
	s_waitcnt lgkmcnt(0)
	v_mfma_f32_16x16x32_bf16 v[116:119], v[206:209], v[164:167], v[116:119]
	v_mfma_f32_16x16x32_bf16 v[112:115], v[214:217], v[164:167], v[112:115]
	v_mfma_f32_16x16x32_bf16 v[100:103], v[206:209], v[172:175], v[100:103]
	v_mfma_f32_16x16x32_bf16 v[96:99], v[214:217], v[172:175], v[96:99]
	v_mfma_f32_16x16x32_bf16 v[84:87], v[206:209], v[180:183], v[84:87]
	v_mfma_f32_16x16x32_bf16 v[80:83], v[214:217], v[180:183], v[80:83]
	v_mfma_f32_16x16x32_bf16 v[68:71], v[206:209], v[188:191], v[68:71]
	v_mfma_f32_16x16x32_bf16 v[64:67], v[214:217], v[188:191], v[64:67]
	v_mfma_f32_16x16x32_bf16 v[116:119], v[210:213], v[168:171], v[116:119]
	v_mfma_f32_16x16x32_bf16 v[112:115], v[218:221], v[168:171], v[112:115]
	v_mfma_f32_16x16x32_bf16 v[100:103], v[210:213], v[176:179], v[100:103]
	v_mfma_f32_16x16x32_bf16 v[96:99], v[218:221], v[176:179], v[96:99]
	v_mfma_f32_16x16x32_bf16 v[84:87], v[210:213], v[184:187], v[84:87]
	v_mfma_f32_16x16x32_bf16 v[80:83], v[218:221], v[184:187], v[80:83]
	v_mfma_f32_16x16x32_bf16 v[68:71], v[210:213], v[202:205], v[68:71]
	v_mfma_f32_16x16x32_bf16 v[64:67], v[218:221], v[202:205], v[64:67]
	s_barrier
	s_mov_b32 m0, s88
	s_nop 0
	global_load_lds_dwordx4 v194, s[80:81]
	s_add_i32 m0, s88, 0x2000
	s_nop 0
	global_load_lds_dwordx4 v132, s[80:81]
	s_mov_b32 m0, s31
	ds_read_b128 v[164:167], v150 offset:49152
	ds_read_b128 v[168:171], v150 offset:50176
	ds_read_b128 v[172:175], v150 offset:51200
	ds_read_b128 v[176:179], v150 offset:52224
	ds_read_b128 v[180:183], v150 offset:53248
	ds_read_b128 v[184:187], v150 offset:54272
	ds_read_b128 v[188:191], v150 offset:55296
	global_load_lds_dwordx4 v128, s[82:83]
	s_mov_b32 m0, s33
	ds_read_b128 v[202:205], v150 offset:56320
	global_load_lds_dwordx4 v130, s[82:83]
	s_mov_b32 m0, s89
	s_nop 0
	global_load_lds_dwordx4 v194, s[84:85]
	s_add_i32 m0, s89, 0x2000
	s_nop 0
	global_load_lds_dwordx4 v132, s[84:85]
	s_waitcnt vmcnt(8)
	s_barrier
	s_waitcnt lgkmcnt(0)
	v_mfma_f32_16x16x32_bf16 v[60:63], v[138:141], v[164:167], v[60:63]
	v_mfma_f32_16x16x32_bf16 v[56:59], v[156:159], v[164:167], v[56:59]
	v_mfma_f32_16x16x32_bf16 v[44:47], v[138:141], v[172:175], v[44:47]
	v_mfma_f32_16x16x32_bf16 v[40:43], v[156:159], v[172:175], v[40:43]
	v_mfma_f32_16x16x32_bf16 v[28:31], v[138:141], v[180:183], v[28:31]
	v_mfma_f32_16x16x32_bf16 v[24:27], v[156:159], v[180:183], v[24:27]
	v_mfma_f32_16x16x32_bf16 v[12:15], v[138:141], v[188:191], v[12:15]
	v_mfma_f32_16x16x32_bf16 v[8:11], v[156:159], v[188:191], v[8:11]
	v_mfma_f32_16x16x32_bf16 v[60:63], v[152:155], v[168:171], v[60:63]
	v_mfma_f32_16x16x32_bf16 v[56:59], v[160:163], v[168:171], v[56:59]
	v_mfma_f32_16x16x32_bf16 v[44:47], v[152:155], v[176:179], v[44:47]
	v_mfma_f32_16x16x32_bf16 v[40:43], v[160:163], v[176:179], v[40:43]
	v_mfma_f32_16x16x32_bf16 v[28:31], v[152:155], v[184:187], v[28:31]
	v_mfma_f32_16x16x32_bf16 v[24:27], v[160:163], v[184:187], v[24:27]
	v_mfma_f32_16x16x32_bf16 v[12:15], v[152:155], v[202:205], v[12:15]
	v_mfma_f32_16x16x32_bf16 v[8:11], v[160:163], v[202:205], v[8:11]
	v_mfma_f32_16x16x32_bf16 v[52:55], v[206:209], v[164:167], v[52:55]
	v_mfma_f32_16x16x32_bf16 v[48:51], v[214:217], v[164:167], v[48:51]
	v_mfma_f32_16x16x32_bf16 v[36:39], v[206:209], v[172:175], v[36:39]
	v_mfma_f32_16x16x32_bf16 v[32:35], v[214:217], v[172:175], v[32:35]
	v_mfma_f32_16x16x32_bf16 v[20:23], v[206:209], v[180:183], v[20:23]
	v_mfma_f32_16x16x32_bf16 v[16:19], v[214:217], v[180:183], v[16:19]
	v_mfma_f32_16x16x32_bf16 v[4:7], v[206:209], v[188:191], v[4:7]
	v_mfma_f32_16x16x32_bf16 v[0:3], v[214:217], v[188:191], v[0:3]
	v_mfma_f32_16x16x32_bf16 v[52:55], v[210:213], v[168:171], v[52:55]
	v_mfma_f32_16x16x32_bf16 v[48:51], v[218:221], v[168:171], v[48:51]
	v_mfma_f32_16x16x32_bf16 v[36:39], v[210:213], v[176:179], v[36:39]
	v_mfma_f32_16x16x32_bf16 v[32:35], v[218:221], v[176:179], v[32:35]
	v_mfma_f32_16x16x32_bf16 v[20:23], v[210:213], v[184:187], v[20:23]
	v_mfma_f32_16x16x32_bf16 v[16:19], v[218:221], v[184:187], v[16:19]
	v_mfma_f32_16x16x32_bf16 v[4:7], v[210:213], v[202:205], v[4:7]
	v_mfma_f32_16x16x32_bf16 v[0:3], v[218:221], v[202:205], v[0:3]
	s_add_u32 s42, s42, 0x100
	s_addc_u32 s43, s43, 0
	s_add_u32 s16, s16, 0x100
	s_addc_u32 s17, s17, 0
	s_cmp_ge_i32 s44, s34
	s_mov_b32 s18, s44
	s_barrier
	s_cbranch_scc0 .LBB0_165

; #define PG8_STAGE(bufoff, gbase, voff) do { _Pragma("unroll") for (int _i = 0; _i < 2; ++_i) \
;         __builtin_amdgcn_global_load_lds((const unsigned*)((const char*)(gbase) + (voff)[_i]), (LAS unsigned*)(lds + (bufoff) + ldsw + _i * 8192), 16, 0, 0); } while (0)
; #define PG8_LDA(dst, b, h) do { _Pragma("unroll") for (int m = 0; m < 4; ++m) _Pragma("unroll") for (int k = 0; k < 2; ++k) dst[m][k] = *(const LAS bf16x8*)(lds + PG8_SA(b, h) + aoff + m * 2048 + k * 1024); } while (0)
; #define PG8_LDB(dst, b, h) do { _Pragma("unroll") for (int n = 0; n < 2; ++n) _Pragma("unroll") for (int k = 0; k < 2; ++k) dst[n][k] = *(const LAS bf16x8*)(lds + PG8_SB(b, h) + boff + n * 2048 + k * 1024); } while (0)
; #define PG8_MMA(ai, bj, At, Bt) do { __builtin_amdgcn_s_setprio(1); _Pragma("unroll") for (int m = 0; m < 4; ++m) _Pragma("unroll") for (int n = 0; n < 2; ++n) _Pragma("unroll") for (int k = 0; k < 2; ++k) \
;         acc[ai][bj][m][n] = __builtin_amdgcn_mfma_f32_16x16x32_bf16(Bt[n][k], At[m][k], acc[ai][bj][m][n], 0, 0, 0); __builtin_amdgcn_s_setprio(0); } while (0)
; #define PG8_WAIT_V(n) asm volatile("s_waitcnt vmcnt(" #n ")" ::: "memory")
; #define PG8_WAIT_L(n) asm volatile("s_waitcnt lgkmcnt(" #n ")" ::: "memory")
; template <class Epi>
; __device__ __forceinline__ void gemm_phase(LAS unsigned char* lds, const Gemm g, const StaticOrder& S, const Epi& E) {
;     ...
;         for (int t = 0; t < nt; t += 2) {
;             const bool last = (t == nt - 2);
;             const char* a1 = cA + (size_t)(t + 1) * kstep;
;             const char* a2 = last ? nA : cA + (size_t)(t + 2) * kstep; const char* b2 = last ? nB : cB + (size_t)(t + 2) * kstep;
;             const char* a3 = a2 + kstep; const char* b3 = b2 + kstep;
;             PG8_LDB(B0, 0, 0); PG8_SCHED; PG8_LDA(At, 0, 0); PG8_STAGE(PG8_SA(1, 1), a1 + hstep, voffA);
;             PG8_WAIT_L(8); PG8_BAR; PG8_WAIT_L(0); PG8_MMA(0, 0, At, B0); PG8_BAR; PG8_SCHED;
;             PG8_LDB(B1, 0, 1); PG8_STAGE(PG8_SB(0, 0), b2, voffB);
;             PG8_BAR; PG8_WAIT_L(0); PG8_MMA(0, 1, At, B1); PG8_BAR;
;             PG8_LDA(At, 0, 1); PG8_STAGE(PG8_SA(0, 0), a2, voffA);
;             PG8_BAR; PG8_WAIT_L(0); PG8_MMA(1, 0, At, B0); PG8_BAR; PG8_SCHED;
;             PG8_STAGE(PG8_SB(0, 1), b2 + hstep, voffB);
;             PG8_WAIT_V(6); PG8_BAR; PG8_MMA(1, 1, At, B1); PG8_BAR;
.LBB0_528:
	s_add_i32 s42, s18, 2
	s_add_u32 s20, s16, 0x80
	s_addc_u32 s19, s17, 0
	ds_read_b128 v[138:141], v224
	ds_read_b128 v[150:153], v224 offset:1024
	ds_read_b128 v[154:157], v224 offset:2048
	ds_read_b128 v[158:161], v224 offset:3072
	s_cmp_eq_u32 s33, s18
	s_cselect_b32 s18, s10, s20
	s_cselect_b32 s19, s11, s19
	s_cselect_b32 s21, s13, s41
	s_cselect_b32 s20, s12, s40
	s_add_i32 m0, s25, 0xc000
	ds_read_b128 v[162:165], v148
	ds_read_b128 v[166:169], v148 offset:1024
	ds_read_b128 v[170:173], v148 offset:2048
	ds_read_b128 v[174:177], v148 offset:3072
	ds_read_b128 v[178:181], v148 offset:4096
	ds_read_b128 v[182:185], v148 offset:5120
	ds_read_b128 v[186:189], v148 offset:6144
	global_load_lds_dwordx4 v136, s[16:17]
	s_add_i32 m0, s25, 0xe000
	ds_read_b128 v[202:205], v148 offset:7168
	global_load_lds_dwordx4 v134, s[16:17]
	s_waitcnt lgkmcnt(11)
	ds_read_b128 v[206:209], v225
	ds_read_b128 v[210:213], v225 offset:1024
	ds_read_b128 v[214:217], v225 offset:2048
	ds_read_b128 v[218:221], v225 offset:3072
	s_waitcnt vmcnt(8)
	s_barrier
	s_waitcnt lgkmcnt(4)
	v_mfma_f32_16x16x32_bf16 v[124:127], v[138:141], v[162:165], v[124:127]
	v_mfma_f32_16x16x32_bf16 v[120:123], v[154:157], v[162:165], v[120:123]
	v_mfma_f32_16x16x32_bf16 v[108:111], v[138:141], v[170:173], v[108:111]
	v_mfma_f32_16x16x32_bf16 v[104:107], v[154:157], v[170:173], v[104:107]
	v_mfma_f32_16x16x32_bf16 v[92:95], v[138:141], v[178:181], v[92:95]
	v_mfma_f32_16x16x32_bf16 v[88:91], v[154:157], v[178:181], v[88:91]
	v_mfma_f32_16x16x32_bf16 v[76:79], v[138:141], v[186:189], v[76:79]
	v_mfma_f32_16x16x32_bf16 v[72:75], v[154:157], v[186:189], v[72:75]
	v_mfma_f32_16x16x32_bf16 v[124:127], v[150:153], v[166:169], v[124:127]
	v_mfma_f32_16x16x32_bf16 v[120:123], v[158:161], v[166:169], v[120:123]
	v_mfma_f32_16x16x32_bf16 v[108:111], v[150:153], v[174:177], v[108:111]
	v_mfma_f32_16x16x32_bf16 v[104:107], v[158:161], v[174:177], v[104:107]
	v_mfma_f32_16x16x32_bf16 v[92:95], v[150:153], v[182:185], v[92:95]
	v_mfma_f32_16x16x32_bf16 v[88:91], v[158:161], v[182:185], v[88:91]
	v_mfma_f32_16x16x32_bf16 v[76:79], v[150:153], v[202:205], v[76:79]
	v_mfma_f32_16x16x32_bf16 v[72:75], v[158:161], v[202:205], v[72:75]
	s_waitcnt lgkmcnt(0)
	v_mfma_f32_16x16x32_bf16 v[116:119], v[206:209], v[162:165], v[116:119]
	v_mfma_f32_16x16x32_bf16 v[112:115], v[214:217], v[162:165], v[112:115]
	v_mfma_f32_16x16x32_bf16 v[100:103], v[206:209], v[170:173], v[100:103]
	v_mfma_f32_16x16x32_bf16 v[96:99], v[214:217], v[170:173], v[96:99]
	v_mfma_f32_16x16x32_bf16 v[84:87], v[206:209], v[178:181], v[84:87]
	v_mfma_f32_16x16x32_bf16 v[80:83], v[214:217], v[178:181], v[80:83]
	v_mfma_f32_16x16x32_bf16 v[68:71], v[206:209], v[186:189], v[68:71]
	v_mfma_f32_16x16x32_bf16 v[64:67], v[214:217], v[186:189], v[64:67]
	v_mfma_f32_16x16x32_bf16 v[116:119], v[210:213], v[166:169], v[116:119]
	v_mfma_f32_16x16x32_bf16 v[112:115], v[218:221], v[166:169], v[112:115]
	v_mfma_f32_16x16x32_bf16 v[100:103], v[210:213], v[174:177], v[100:103]
	v_mfma_f32_16x16x32_bf16 v[96:99], v[218:221], v[174:177], v[96:99]
	v_mfma_f32_16x16x32_bf16 v[84:87], v[210:213], v[182:185], v[84:87]
	v_mfma_f32_16x16x32_bf16 v[80:83], v[218:221], v[182:185], v[80:83]
	v_mfma_f32_16x16x32_bf16 v[68:71], v[210:213], v[202:205], v[68:71]
	v_mfma_f32_16x16x32_bf16 v[64:67], v[218:221], v[202:205], v[64:67]
	s_barrier
	s_add_u32 s80, s20, 0x80
	s_addc_u32 s81, s21, 0
	s_mov_b32 m0, s86
	s_nop 0
	global_load_lds_dwordx4 v194, s[20:21]
	s_add_i32 m0, s86, 0x2000
	s_nop 0
	global_load_lds_dwordx4 v132, s[20:21]
	s_mov_b32 m0, s25
	s_add_u32 s82, s18, 0x80
	s_addc_u32 s83, s19, 0
	ds_read_b128 v[162:165], v148 offset:16384
	ds_read_b128 v[166:169], v148 offset:17408
	ds_read_b128 v[170:173], v148 offset:18432
	ds_read_b128 v[174:177], v148 offset:19456
	ds_read_b128 v[178:181], v148 offset:20480
	ds_read_b128 v[182:185], v148 offset:21504
	ds_read_b128 v[186:189], v148 offset:22528
	global_load_lds_dwordx4 v128, s[18:19]
	s_mov_b32 m0, s26
	ds_read_b128 v[202:205], v148 offset:23552
	global_load_lds_dwordx4 v130, s[18:19]
	s_add_u32 s20, s20, s2
	s_addc_u32 s21, s21, s3
	s_add_u32 s84, s20, 0x80
	s_mov_b32 m0, s87
	s_addc_u32 s85, s21, 0
	global_load_lds_dwordx4 v194, s[20:21]
	s_add_i32 m0, s87, 0x2000
	s_nop 0
	global_load_lds_dwordx4 v132, s[20:21]
	s_waitcnt vmcnt(8)
	s_barrier
	s_waitcnt lgkmcnt(0)
	v_mfma_f32_16x16x32_bf16 v[60:63], v[138:141], v[162:165], v[60:63]
	v_mfma_f32_16x16x32_bf16 v[56:59], v[154:157], v[162:165], v[56:59]
	v_mfma_f32_16x16x32_bf16 v[44:47], v[138:141], v[170:173], v[44:47]
	v_mfma_f32_16x16x32_bf16 v[40:43], v[154:157], v[170:173], v[40:43]
	v_mfma_f32_16x16x32_bf16 v[28:31], v[138:141], v[178:181], v[28:31]
	v_mfma_f32_16x16x32_bf16 v[24:27], v[154:157], v[178:181], v[24:27]
	v_mfma_f32_16x16x32_bf16 v[12:15], v[138:141], v[186:189], v[12:15]
	v_mfma_f32_16x16x32_bf16 v[8:11], v[154:157], v[186:189], v[8:11]
	v_mfma_f32_16x16x32_bf16 v[60:63], v[150:153], v[166:169], v[60:63]
	v_mfma_f32_16x16x32_bf16 v[56:59], v[158:161], v[166:169], v[56:59]
	v_mfma_f32_16x16x32_bf16 v[44:47], v[150:153], v[174:177], v[44:47]
	v_mfma_f32_16x16x32_bf16 v[40:43], v[158:161], v[174:177], v[40:43]
	v_mfma_f32_16x16x32_bf16 v[28:31], v[150:153], v[182:185], v[28:31]
	v_mfma_f32_16x16x32_bf16 v[24:27], v[158:161], v[182:185], v[24:27]
	v_mfma_f32_16x16x32_bf16 v[12:15], v[150:153], v[202:205], v[12:15]
	v_mfma_f32_16x16x32_bf16 v[8:11], v[158:161], v[202:205], v[8:11]
	v_mfma_f32_16x16x32_bf16 v[52:55], v[206:209], v[162:165], v[52:55]
	v_mfma_f32_16x16x32_bf16 v[48:51], v[214:217], v[162:165], v[48:51]
	v_mfma_f32_16x16x32_bf16 v[36:39], v[206:209], v[170:173], v[36:39]
	v_mfma_f32_16x16x32_bf16 v[32:35], v[214:217], v[170:173], v[32:35]
	v_mfma_f32_16x16x32_bf16 v[20:23], v[206:209], v[178:181], v[20:23]
	v_mfma_f32_16x16x32_bf16 v[16:19], v[214:217], v[178:181], v[16:19]
	v_mfma_f32_16x16x32_bf16 v[4:7], v[206:209], v[186:189], v[4:7]
	v_mfma_f32_16x16x32_bf16 v[0:3], v[214:217], v[186:189], v[0:3]
	v_mfma_f32_16x16x32_bf16 v[52:55], v[210:213], v[166:169], v[52:55]
	v_mfma_f32_16x16x32_bf16 v[48:51], v[218:221], v[166:169], v[48:51]
	v_mfma_f32_16x16x32_bf16 v[36:39], v[210:213], v[174:177], v[36:39]
	v_mfma_f32_16x16x32_bf16 v[32:35], v[218:221], v[174:177], v[32:35]
	v_mfma_f32_16x16x32_bf16 v[20:23], v[210:213], v[182:185], v[20:23]
	v_mfma_f32_16x16x32_bf16 v[16:19], v[218:221], v[182:185], v[16:19]
	v_mfma_f32_16x16x32_bf16 v[4:7], v[210:213], v[202:205], v[4:7]
	v_mfma_f32_16x16x32_bf16 v[0:3], v[218:221], v[202:205], v[0:3]
	s_barrier
; #define PG8_STAGE(bufoff, gbase, voff) do { _Pragma("unroll") for (int _i = 0; _i < 2; ++_i) \
;         __builtin_amdgcn_global_load_lds((const unsigned*)((const char*)(gbase) + (voff)[_i]), (LAS unsigned*)(lds + (bufoff) + ldsw + _i * 8192), 16, 0, 0); } while (0)
; #define PG8_LDA(dst, b, h) do { _Pragma("unroll") for (int m = 0; m < 4; ++m) _Pragma("unroll") for (int k = 0; k < 2; ++k) dst[m][k] = *(const LAS bf16x8*)(lds + PG8_SA(b, h) + aoff + m * 2048 + k * 1024); } while (0)
; #define PG8_LDB(dst, b, h) do { _Pragma("unroll") for (int n = 0; n < 2; ++n) _Pragma("unroll") for (int k = 0; k < 2; ++k) dst[n][k] = *(const LAS bf16x8*)(lds + PG8_SB(b, h) + boff + n * 2048 + k * 1024); } while (0)
; #define PG8_MMA(ai, bj, At, Bt) do { __builtin_amdgcn_s_setprio(1); _Pragma("unroll") for (int m = 0; m < 4; ++m) _Pragma("unroll") for (int n = 0; n < 2; ++n) _Pragma("unroll") for (int k = 0; k < 2; ++k) \
;         acc[ai][bj][m][n] = __builtin_amdgcn_mfma_f32_16x16x32_bf16(Bt[n][k], At[m][k], acc[ai][bj][m][n], 0, 0, 0); __builtin_amdgcn_s_setprio(0); } while (0)
; #define PG8_WAIT_V(n) asm volatile("s_waitcnt vmcnt(" #n ")" ::: "memory")
; #define PG8_WAIT_L(n) asm volatile("s_waitcnt lgkmcnt(" #n ")" ::: "memory")
; #define PG8_BAR __builtin_amdgcn_s_barrier()
; #define PG8_SCHED __builtin_amdgcn_sched_barrier(0)
; template <class Epi>
; __device__ __forceinline__ void gemm_phase(LAS unsigned char* lds, const Gemm g, const StaticOrder& S, const Epi& E) {
;     ...
;             PG8_LDB(B0, 1, 0); PG8_SCHED; PG8_LDA(At, 1, 0); PG8_STAGE(PG8_SA(0, 1), a2 + hstep, voffA);
;             PG8_WAIT_L(8); PG8_BAR; PG8_WAIT_L(0); PG8_MMA(0, 0, At, B0); PG8_BAR; PG8_SCHED;
;             PG8_LDB(B1, 1, 1); PG8_STAGE(PG8_SB(1, 0), b3, voffB);
;             PG8_BAR; PG8_WAIT_L(0); PG8_MMA(0, 1, At, B1); PG8_BAR;
;             PG8_LDA(At, 1, 1); PG8_STAGE(PG8_SA(1, 0), a3, voffA);
;             PG8_BAR; PG8_WAIT_L(0); PG8_MMA(1, 0, At, B0); PG8_BAR; PG8_SCHED;
;             PG8_STAGE(PG8_SB(1, 1), b3 + hstep, voffB);
;             PG8_WAIT_V(6); PG8_BAR; PG8_MMA(1, 1, At, B1); PG8_BAR;
	ds_read_b128 v[138:141], v226
	ds_read_b128 v[150:153], v226 offset:1024
	ds_read_b128 v[154:157], v226 offset:2048
	ds_read_b128 v[158:161], v226 offset:3072
	s_add_u32 s18, s18, s2
	s_addc_u32 s19, s19, s3
	s_mov_b32 m0, s27
	ds_read_b128 v[162:165], v148 offset:32768
	ds_read_b128 v[166:169], v148 offset:33792
	ds_read_b128 v[170:173], v148 offset:34816
	ds_read_b128 v[174:177], v148 offset:35840
	ds_read_b128 v[178:181], v148 offset:36864
	ds_read_b128 v[182:185], v148 offset:37888
	ds_read_b128 v[186:189], v148 offset:38912
	global_load_lds_dwordx4 v128, s[18:19]
	s_mov_b32 m0, s28
	ds_read_b128 v[202:205], v148 offset:39936
	global_load_lds_dwordx4 v130, s[18:19]
	s_waitcnt lgkmcnt(11)
	ds_read_b128 v[206:209], v227
	ds_read_b128 v[210:213], v227 offset:1024
	ds_read_b128 v[214:217], v227 offset:2048
	ds_read_b128 v[218:221], v227 offset:3072
	s_waitcnt vmcnt(8)
	s_barrier
	s_waitcnt lgkmcnt(4)
	v_mfma_f32_16x16x32_bf16 v[124:127], v[138:141], v[162:165], v[124:127]
	v_mfma_f32_16x16x32_bf16 v[120:123], v[154:157], v[162:165], v[120:123]
	v_mfma_f32_16x16x32_bf16 v[108:111], v[138:141], v[170:173], v[108:111]
	v_mfma_f32_16x16x32_bf16 v[104:107], v[154:157], v[170:173], v[104:107]
	v_mfma_f32_16x16x32_bf16 v[92:95], v[138:141], v[178:181], v[92:95]
	v_mfma_f32_16x16x32_bf16 v[88:91], v[154:157], v[178:181], v[88:91]
	v_mfma_f32_16x16x32_bf16 v[76:79], v[138:141], v[186:189], v[76:79]
	v_mfma_f32_16x16x32_bf16 v[72:75], v[154:157], v[186:189], v[72:75]
	v_mfma_f32_16x16x32_bf16 v[124:127], v[150:153], v[166:169], v[124:127]
	v_mfma_f32_16x16x32_bf16 v[120:123], v[158:161], v[166:169], v[120:123]
	v_mfma_f32_16x16x32_bf16 v[108:111], v[150:153], v[174:177], v[108:111]
	v_mfma_f32_16x16x32_bf16 v[104:107], v[158:161], v[174:177], v[104:107]
	v_mfma_f32_16x16x32_bf16 v[92:95], v[150:153], v[182:185], v[92:95]
	v_mfma_f32_16x16x32_bf16 v[88:91], v[158:161], v[182:185], v[88:91]
	v_mfma_f32_16x16x32_bf16 v[76:79], v[150:153], v[202:205], v[76:79]
	v_mfma_f32_16x16x32_bf16 v[72:75], v[158:161], v[202:205], v[72:75]
	s_waitcnt lgkmcnt(0)
	v_mfma_f32_16x16x32_bf16 v[116:119], v[206:209], v[162:165], v[116:119]
	v_mfma_f32_16x16x32_bf16 v[112:115], v[214:217], v[162:165], v[112:115]
	v_mfma_f32_16x16x32_bf16 v[100:103], v[206:209], v[170:173], v[100:103]
	v_mfma_f32_16x16x32_bf16 v[96:99], v[214:217], v[170:173], v[96:99]
	v_mfma_f32_16x16x32_bf16 v[84:87], v[206:209], v[178:181], v[84:87]
	v_mfma_f32_16x16x32_bf16 v[80:83], v[214:217], v[178:181], v[80:83]
	v_mfma_f32_16x16x32_bf16 v[68:71], v[206:209], v[186:189], v[68:71]
	v_mfma_f32_16x16x32_bf16 v[64:67], v[214:217], v[186:189], v[64:67]
	v_mfma_f32_16x16x32_bf16 v[116:119], v[210:213], v[166:169], v[116:119]
	v_mfma_f32_16x16x32_bf16 v[112:115], v[218:221], v[166:169], v[112:115]
	v_mfma_f32_16x16x32_bf16 v[100:103], v[210:213], v[174:177], v[100:103]
	v_mfma_f32_16x16x32_bf16 v[96:99], v[218:221], v[174:177], v[96:99]
	v_mfma_f32_16x16x32_bf16 v[84:87], v[210:213], v[182:185], v[84:87]
	v_mfma_f32_16x16x32_bf16 v[80:83], v[218:221], v[182:185], v[80:83]
	v_mfma_f32_16x16x32_bf16 v[68:71], v[210:213], v[202:205], v[68:71]
	v_mfma_f32_16x16x32_bf16 v[64:67], v[218:221], v[202:205], v[64:67]
	s_barrier
	s_mov_b32 m0, s88
	s_nop 0
	global_load_lds_dwordx4 v194, s[80:81]
	s_add_i32 m0, s88, 0x2000
	s_nop 0
	global_load_lds_dwordx4 v132, s[80:81]
	s_mov_b32 m0, s29
	ds_read_b128 v[162:165], v148 offset:49152
	ds_read_b128 v[166:169], v148 offset:50176
	ds_read_b128 v[170:173], v148 offset:51200
	ds_read_b128 v[174:177], v148 offset:52224
	ds_read_b128 v[178:181], v148 offset:53248
	ds_read_b128 v[182:185], v148 offset:54272
	ds_read_b128 v[186:189], v148 offset:55296
	global_load_lds_dwordx4 v128, s[82:83]
	s_mov_b32 m0, s30
	ds_read_b128 v[202:205], v148 offset:56320
	global_load_lds_dwordx4 v130, s[82:83]
	s_mov_b32 m0, s89
	s_nop 0
	global_load_lds_dwordx4 v194, s[84:85]
	s_add_i32 m0, s89, 0x2000
	s_nop 0
	global_load_lds_dwordx4 v132, s[84:85]
	s_waitcnt vmcnt(8)
	s_barrier
	s_waitcnt lgkmcnt(0)
	v_mfma_f32_16x16x32_bf16 v[60:63], v[138:141], v[162:165], v[60:63]
	v_mfma_f32_16x16x32_bf16 v[56:59], v[154:157], v[162:165], v[56:59]
	v_mfma_f32_16x16x32_bf16 v[44:47], v[138:141], v[170:173], v[44:47]
	v_mfma_f32_16x16x32_bf16 v[40:43], v[154:157], v[170:173], v[40:43]
	v_mfma_f32_16x16x32_bf16 v[28:31], v[138:141], v[178:181], v[28:31]
	v_mfma_f32_16x16x32_bf16 v[24:27], v[154:157], v[178:181], v[24:27]
	v_mfma_f32_16x16x32_bf16 v[12:15], v[138:141], v[186:189], v[12:15]
	v_mfma_f32_16x16x32_bf16 v[8:11], v[154:157], v[186:189], v[8:11]
	v_mfma_f32_16x16x32_bf16 v[60:63], v[150:153], v[166:169], v[60:63]
	v_mfma_f32_16x16x32_bf16 v[56:59], v[158:161], v[166:169], v[56:59]
	v_mfma_f32_16x16x32_bf16 v[44:47], v[150:153], v[174:177], v[44:47]
	v_mfma_f32_16x16x32_bf16 v[40:43], v[158:161], v[174:177], v[40:43]
	v_mfma_f32_16x16x32_bf16 v[28:31], v[150:153], v[182:185], v[28:31]
	v_mfma_f32_16x16x32_bf16 v[24:27], v[158:161], v[182:185], v[24:27]
	v_mfma_f32_16x16x32_bf16 v[12:15], v[150:153], v[202:205], v[12:15]
	v_mfma_f32_16x16x32_bf16 v[8:11], v[158:161], v[202:205], v[8:11]
	v_mfma_f32_16x16x32_bf16 v[52:55], v[206:209], v[162:165], v[52:55]
	v_mfma_f32_16x16x32_bf16 v[48:51], v[214:217], v[162:165], v[48:51]
	v_mfma_f32_16x16x32_bf16 v[36:39], v[206:209], v[170:173], v[36:39]
	v_mfma_f32_16x16x32_bf16 v[32:35], v[214:217], v[170:173], v[32:35]
	v_mfma_f32_16x16x32_bf16 v[20:23], v[206:209], v[178:181], v[20:23]
	v_mfma_f32_16x16x32_bf16 v[16:19], v[214:217], v[178:181], v[16:19]
	v_mfma_f32_16x16x32_bf16 v[4:7], v[206:209], v[186:189], v[4:7]
	v_mfma_f32_16x16x32_bf16 v[0:3], v[214:217], v[186:189], v[0:3]
	v_mfma_f32_16x16x32_bf16 v[52:55], v[210:213], v[166:169], v[52:55]
	v_mfma_f32_16x16x32_bf16 v[48:51], v[218:221], v[166:169], v[48:51]
	v_mfma_f32_16x16x32_bf16 v[36:39], v[210:213], v[174:177], v[36:39]
	v_mfma_f32_16x16x32_bf16 v[32:35], v[218:221], v[174:177], v[32:35]
	v_mfma_f32_16x16x32_bf16 v[20:23], v[210:213], v[182:185], v[20:23]
	v_mfma_f32_16x16x32_bf16 v[16:19], v[218:221], v[182:185], v[16:19]
	v_mfma_f32_16x16x32_bf16 v[4:7], v[210:213], v[202:205], v[4:7]
	v_mfma_f32_16x16x32_bf16 v[0:3], v[218:221], v[202:205], v[0:3]
	s_add_u32 s40, s40, 0x100
	s_addc_u32 s41, s41, 0
	s_add_u32 s16, s16, 0x100
	s_addc_u32 s17, s17, 0
	s_cmp_ge_i32 s42, s31
	s_mov_b32 s18, s42
	s_barrier
	s_cbranch_scc0 .LBB0_528
